# MO8+TRIM + IL (SP2 load segments: LDS reads interleaved with the LDS-DMA loads) + ROT2 (loop-edge SALU moved into the previous load segment)
# baseline (speedup 1.0000x reference)
.LBB0_139:
	s_add_i32 s49, 0, 0x10000
	s_add_i32 s52, 0, 0x14000
	v_add_u32_e32 v156, s49, v145
	v_add_u32_e32 v172, s52, v145
	ds_read_b128 v[140:143], v156
	ds_read_b128 v[148:151], v156 offset:1024
	ds_read_b128 v[152:155], v156 offset:2048
	ds_read_b128 v[156:159], v156 offset:3072
	ds_read_b128 v[160:163], v172
	ds_read_b128 v[164:167], v172 offset:1024
	ds_read_b128 v[168:171], v172 offset:2048
	ds_read_b128 v[190:193], v172 offset:3072
	v_lshl_add_u64 v[172:173], s[18:19], 0, v[136:137]
	s_add_i32 m0, s31, 0xc000
	ds_read_b128 v[194:197], v147
	ds_read_b128 v[198:201], v147 offset:1024
	ds_read_b128 v[202:205], v147 offset:2048
	ds_read_b128 v[206:209], v147 offset:3072
	ds_read_b128 v[228:231], v147 offset:4096
	ds_read_b128 v[232:235], v147 offset:5120
	ds_read_b128 v[236:239], v147 offset:6144
	ds_read_b128 v[240:243], v147 offset:7168
	global_load_lds_dwordx4 v[172:173], off
	v_lshl_add_u64 v[172:173], s[18:19], 0, v[138:139]
	s_add_i32 m0, s31, 0xe000
	s_nop 0
	global_load_lds_dwordx4 v[172:173], off
	s_waitcnt vmcnt(8)
	s_waitcnt lgkmcnt(0)
	s_setprio 1
	s_barrier
	v_mfma_f32_16x16x32_bf16 v[126:129], v[140:143], v[194:197], v[126:129]
	v_mfma_f32_16x16x32_bf16 v[126:129], v[148:151], v[198:201], v[126:129]
	v_mfma_f32_16x16x32_bf16 v[118:121], v[148:151], v[206:209], v[118:121]
	v_mfma_f32_16x16x32_bf16 v[118:121], v[140:143], v[202:205], v[118:121]
	v_mfma_f32_16x16x32_bf16 v[102:105], v[140:143], v[228:231], v[102:105]
	v_mfma_f32_16x16x32_bf16 v[102:105], v[148:151], v[232:235], v[102:105]
	v_mfma_f32_16x16x32_bf16 v[86:89], v[148:151], v[240:243], v[86:89]
	v_mfma_f32_16x16x32_bf16 v[86:89], v[140:143], v[236:239], v[86:89]
	v_mfma_f32_16x16x32_bf16 v[78:81], v[152:155], v[236:239], v[78:81]
	v_mfma_f32_16x16x32_bf16 v[78:81], v[156:159], v[240:243], v[78:81]
	v_mfma_f32_16x16x32_bf16 v[94:97], v[156:159], v[232:235], v[94:97]
	v_mfma_f32_16x16x32_bf16 v[94:97], v[152:155], v[228:231], v[94:97]
	v_mfma_f32_16x16x32_bf16 v[110:113], v[152:155], v[202:205], v[110:113]
	v_mfma_f32_16x16x32_bf16 v[110:113], v[156:159], v[206:209], v[110:113]
	v_mfma_f32_16x16x32_bf16 v[122:125], v[156:159], v[198:201], v[122:125]
	v_mfma_f32_16x16x32_bf16 v[122:125], v[152:155], v[194:197], v[122:125]
	v_mfma_f32_16x16x32_bf16 v[114:117], v[160:163], v[194:197], v[114:117]
	v_mfma_f32_16x16x32_bf16 v[114:117], v[164:167], v[198:201], v[114:117]
	v_mfma_f32_16x16x32_bf16 v[98:101], v[164:167], v[206:209], v[98:101]
	v_mfma_f32_16x16x32_bf16 v[98:101], v[160:163], v[202:205], v[98:101]
	v_mfma_f32_16x16x32_bf16 v[82:85], v[160:163], v[228:231], v[82:85]
	v_mfma_f32_16x16x32_bf16 v[82:85], v[164:167], v[232:235], v[82:85]
	v_mfma_f32_16x16x32_bf16 v[70:73], v[164:167], v[240:243], v[70:73]
	v_mfma_f32_16x16x32_bf16 v[70:73], v[160:163], v[236:239], v[70:73]
	v_mfma_f32_16x16x32_bf16 v[66:69], v[168:171], v[236:239], v[66:69]
	v_mfma_f32_16x16x32_bf16 v[66:69], v[190:193], v[240:243], v[66:69]
	v_mfma_f32_16x16x32_bf16 v[74:77], v[190:193], v[232:235], v[74:77]
	v_mfma_f32_16x16x32_bf16 v[74:77], v[168:171], v[228:231], v[74:77]
	v_mfma_f32_16x16x32_bf16 v[90:93], v[168:171], v[202:205], v[90:93]
	v_mfma_f32_16x16x32_bf16 v[90:93], v[190:193], v[206:209], v[90:93]
	v_mfma_f32_16x16x32_bf16 v[106:109], v[190:193], v[198:201], v[106:109]
	v_mfma_f32_16x16x32_bf16 v[106:109], v[168:171], v[194:197], v[106:109]
	s_barrier
	s_setprio 0
	s_add_i32 s49, s49, s26
	v_lshl_add_u64 v[172:173], s[22:23], 0, v[0:1]
	s_mov_b32 m0, s49
	s_nop 0
	global_load_lds_dwordx4 v[172:173], off
	ds_read_b128 v[194:197], v147 offset:16384
	ds_read_b128 v[198:201], v147 offset:17408
	s_add_i32 m0, s49, 0x2000
	s_add_u32 s50, s22, 0x100000
	v_lshl_add_u64 v[178:179], s[22:23], 0, v[130:131]
	s_addc_u32 s51, s23, 0
	s_add_i32 s49, s52, s26
	global_load_lds_dwordx4 v[178:179], off
	ds_read_b128 v[202:205], v147 offset:18432
	ds_read_b128 v[206:209], v147 offset:19456
	v_lshl_add_u64 v[180:181], s[50:51], 0, v[0:1]
	s_mov_b32 m0, s49
	v_lshl_add_u64 v[210:211], s[24:25], 0, v[132:133]
	global_load_lds_dwordx4 v[180:181], off
	ds_read_b128 v[228:231], v147 offset:20480
	ds_read_b128 v[232:235], v147 offset:21504
	v_lshl_add_u64 v[180:181], s[50:51], 0, v[130:131]
	s_add_i32 m0, s49, 0x2000
	s_nop 0
	global_load_lds_dwordx4 v[180:181], off
	ds_read_b128 v[236:239], v147 offset:22528
	ds_read_b128 v[240:243], v147 offset:23552
	v_lshl_add_u64 v[180:181], s[24:25], 0, v[134:135]
	s_mov_b32 m0, s31
	s_nop 0
	global_load_lds_dwordx4 v[180:181], off
	s_mov_b32 m0, s36
	s_nop 0
	global_load_lds_dwordx4 v[210:211], off
	s_waitcnt vmcnt(8)
	s_waitcnt lgkmcnt(0)
	s_setprio 1
	s_barrier
	v_mfma_f32_16x16x32_bf16 v[62:65], v[140:143], v[194:197], v[62:65]
	v_mfma_f32_16x16x32_bf16 v[62:65], v[148:151], v[198:201], v[62:65]
	v_mfma_f32_16x16x32_bf16 v[54:57], v[148:151], v[206:209], v[54:57]
	v_mfma_f32_16x16x32_bf16 v[54:57], v[140:143], v[202:205], v[54:57]
	v_mfma_f32_16x16x32_bf16 v[38:41], v[140:143], v[228:231], v[38:41]
	v_mfma_f32_16x16x32_bf16 v[38:41], v[148:151], v[232:235], v[38:41]
	v_mfma_f32_16x16x32_bf16 v[22:25], v[148:151], v[240:243], v[22:25]
	v_mfma_f32_16x16x32_bf16 v[22:25], v[140:143], v[236:239], v[22:25]
	v_mfma_f32_16x16x32_bf16 v[14:17], v[152:155], v[236:239], v[14:17]
	v_mfma_f32_16x16x32_bf16 v[14:17], v[156:159], v[240:243], v[14:17]
	v_mfma_f32_16x16x32_bf16 v[30:33], v[156:159], v[232:235], v[30:33]
	v_mfma_f32_16x16x32_bf16 v[30:33], v[152:155], v[228:231], v[30:33]
	v_mfma_f32_16x16x32_bf16 v[46:49], v[152:155], v[202:205], v[46:49]
	v_mfma_f32_16x16x32_bf16 v[46:49], v[156:159], v[206:209], v[46:49]
	v_mfma_f32_16x16x32_bf16 v[58:61], v[156:159], v[198:201], v[58:61]
	v_mfma_f32_16x16x32_bf16 v[58:61], v[152:155], v[194:197], v[58:61]
	v_mfma_f32_16x16x32_bf16 v[50:53], v[160:163], v[194:197], v[50:53]
	v_mfma_f32_16x16x32_bf16 v[50:53], v[164:167], v[198:201], v[50:53]
	v_mfma_f32_16x16x32_bf16 v[34:37], v[164:167], v[206:209], v[34:37]
	v_mfma_f32_16x16x32_bf16 v[34:37], v[160:163], v[202:205], v[34:37]
	v_mfma_f32_16x16x32_bf16 v[18:21], v[160:163], v[228:231], v[18:21]
	v_mfma_f32_16x16x32_bf16 v[18:21], v[164:167], v[232:235], v[18:21]
	v_mfma_f32_16x16x32_bf16 v[6:9], v[164:167], v[240:243], v[6:9]
	v_mfma_f32_16x16x32_bf16 v[6:9], v[160:163], v[236:239], v[6:9]
	v_mfma_f32_16x16x32_bf16 v[2:5], v[168:171], v[236:239], v[2:5]
	v_mfma_f32_16x16x32_bf16 v[2:5], v[190:193], v[240:243], v[2:5]
	v_mfma_f32_16x16x32_bf16 v[10:13], v[190:193], v[232:235], v[10:13]
	v_mfma_f32_16x16x32_bf16 v[10:13], v[168:171], v[228:231], v[10:13]
	v_mfma_f32_16x16x32_bf16 v[26:29], v[168:171], v[202:205], v[26:29]
	v_mfma_f32_16x16x32_bf16 v[26:29], v[190:193], v[206:209], v[26:29]
	v_mfma_f32_16x16x32_bf16 v[42:45], v[190:193], v[198:201], v[42:45]
	v_mfma_f32_16x16x32_bf16 v[42:45], v[168:171], v[194:197], v[42:45]
	s_barrier
	s_setprio 0
	s_add_i32 s49, 0, 0x18000
	s_add_i32 s50, 0, 0x1c000
	v_add_u32_e32 v156, s49, v145
	v_add_u32_e32 v175, s50, v145
	ds_read_b128 v[140:143], v156
	ds_read_b128 v[148:151], v156 offset:1024
	ds_read_b128 v[152:155], v156 offset:2048
	ds_read_b128 v[156:159], v156 offset:3072
	ds_read_b128 v[160:163], v175
	ds_read_b128 v[164:167], v175 offset:1024
	ds_read_b128 v[168:171], v175 offset:2048
	ds_read_b128 v[190:193], v175 offset:3072
	s_add_u32 s24, s24, 0x100000
	s_addc_u32 s25, s25, 0
	s_mov_b32 m0, s37
	v_lshl_add_u64 v[244:245], s[24:25], 0, v[134:135]
	ds_read_b128 v[194:197], v147 offset:32768
	ds_read_b128 v[198:201], v147 offset:33792
	ds_read_b128 v[202:205], v147 offset:34816
	ds_read_b128 v[206:209], v147 offset:35840
	ds_read_b128 v[228:231], v147 offset:36864
	ds_read_b128 v[232:235], v147 offset:37888
	ds_read_b128 v[236:239], v147 offset:38912
	ds_read_b128 v[240:243], v147 offset:39936
	global_load_lds_dwordx4 v[244:245], off
	v_lshl_add_u64 v[244:245], s[24:25], 0, v[132:133]
	s_mov_b32 m0, s38
	s_nop 0
	global_load_lds_dwordx4 v[244:245], off
	s_waitcnt vmcnt(8)
	s_waitcnt lgkmcnt(0)
	s_setprio 1
	s_barrier
	v_mfma_f32_16x16x32_bf16 v[126:129], v[140:143], v[194:197], v[126:129]
	v_mfma_f32_16x16x32_bf16 v[126:129], v[148:151], v[198:201], v[126:129]
	v_mfma_f32_16x16x32_bf16 v[118:121], v[148:151], v[206:209], v[118:121]
	v_mfma_f32_16x16x32_bf16 v[118:121], v[140:143], v[202:205], v[118:121]
	v_mfma_f32_16x16x32_bf16 v[102:105], v[140:143], v[228:231], v[102:105]
	v_mfma_f32_16x16x32_bf16 v[102:105], v[148:151], v[232:235], v[102:105]
	v_mfma_f32_16x16x32_bf16 v[86:89], v[148:151], v[240:243], v[86:89]
	v_mfma_f32_16x16x32_bf16 v[86:89], v[140:143], v[236:239], v[86:89]
	v_mfma_f32_16x16x32_bf16 v[78:81], v[152:155], v[236:239], v[78:81]
	v_mfma_f32_16x16x32_bf16 v[78:81], v[156:159], v[240:243], v[78:81]
	v_mfma_f32_16x16x32_bf16 v[94:97], v[156:159], v[232:235], v[94:97]
	v_mfma_f32_16x16x32_bf16 v[94:97], v[152:155], v[228:231], v[94:97]
	v_mfma_f32_16x16x32_bf16 v[110:113], v[152:155], v[202:205], v[110:113]
	v_mfma_f32_16x16x32_bf16 v[110:113], v[156:159], v[206:209], v[110:113]
	v_mfma_f32_16x16x32_bf16 v[122:125], v[156:159], v[198:201], v[122:125]
	v_mfma_f32_16x16x32_bf16 v[122:125], v[152:155], v[194:197], v[122:125]
	v_mfma_f32_16x16x32_bf16 v[114:117], v[160:163], v[194:197], v[114:117]
	v_mfma_f32_16x16x32_bf16 v[114:117], v[164:167], v[198:201], v[114:117]
	v_mfma_f32_16x16x32_bf16 v[98:101], v[164:167], v[206:209], v[98:101]
	v_mfma_f32_16x16x32_bf16 v[98:101], v[160:163], v[202:205], v[98:101]
	v_mfma_f32_16x16x32_bf16 v[82:85], v[160:163], v[228:231], v[82:85]
	v_mfma_f32_16x16x32_bf16 v[82:85], v[164:167], v[232:235], v[82:85]
	v_mfma_f32_16x16x32_bf16 v[70:73], v[164:167], v[240:243], v[70:73]
	v_mfma_f32_16x16x32_bf16 v[70:73], v[160:163], v[236:239], v[70:73]
	v_mfma_f32_16x16x32_bf16 v[66:69], v[168:171], v[236:239], v[66:69]
	v_mfma_f32_16x16x32_bf16 v[66:69], v[190:193], v[240:243], v[66:69]
	v_mfma_f32_16x16x32_bf16 v[74:77], v[190:193], v[232:235], v[74:77]
	v_mfma_f32_16x16x32_bf16 v[74:77], v[168:171], v[228:231], v[74:77]
	v_mfma_f32_16x16x32_bf16 v[90:93], v[168:171], v[202:205], v[90:93]
	v_mfma_f32_16x16x32_bf16 v[90:93], v[190:193], v[206:209], v[90:93]
	v_mfma_f32_16x16x32_bf16 v[106:109], v[190:193], v[198:201], v[106:109]
	v_mfma_f32_16x16x32_bf16 v[106:109], v[168:171], v[194:197], v[106:109]
	s_barrier
	s_setprio 0
	s_add_i32 s24, s49, s26
	v_lshl_add_u64 v[172:173], v[172:173], 0, s[34:35]
	s_mov_b32 m0, s24
	s_nop 0
	global_load_lds_dwordx4 v[172:173], off
	ds_read_b128 v[194:197], v147 offset:49152
	ds_read_b128 v[198:201], v147 offset:50176
	s_add_i32 m0, s24, 0x2000
	s_add_u32 s22, s22, 0x100080
	v_lshl_add_u64 v[172:173], v[178:179], 0, s[34:35]
	s_addc_u32 s23, s23, 0
	s_add_i32 s24, s50, s26
	global_load_lds_dwordx4 v[172:173], off
	ds_read_b128 v[202:205], v147 offset:51200
	ds_read_b128 v[206:209], v147 offset:52224
	v_lshl_add_u64 v[172:173], s[22:23], 0, v[0:1]
	s_mov_b32 m0, s24
	s_nop 0
	global_load_lds_dwordx4 v[172:173], off
	ds_read_b128 v[228:231], v147 offset:53248
	ds_read_b128 v[232:235], v147 offset:54272
	v_lshl_add_u64 v[172:173], s[22:23], 0, v[130:131]
	s_add_i32 m0, s24, 0x2000
	s_nop 0
	global_load_lds_dwordx4 v[172:173], off
	ds_read_b128 v[236:239], v147 offset:55296
	ds_read_b128 v[240:243], v147 offset:56320
	v_lshl_add_u64 v[172:173], v[180:181], 0, s[34:35]
	s_mov_b32 m0, s39
	s_nop 0
	global_load_lds_dwordx4 v[172:173], off
	s_add_i32 s48, s48, 2
	s_add_u32 s18, s18, 0x100
	s_addc_u32 s19, s19, 0
	s_add_u32 s46, s46, 0x100
	s_addc_u32 s47, s47, 0
	s_add_u32 s22, s18, 0xfff00080
	s_addc_u32 s23, s19, -1
	s_cmp_eq_u32 s48, 60
	s_cselect_b32 s25, s9, s23
	s_cselect_b32 s24, s44, s22
	s_cselect_b32 s23, s7, s47
	s_cselect_b32 s22, s45, s46
	v_lshl_add_u64 v[172:173], v[210:211], 0, s[34:35]
	s_mov_b32 m0, s40
	s_nop 0
	global_load_lds_dwordx4 v[172:173], off
	s_waitcnt vmcnt(8)
	s_waitcnt lgkmcnt(0)
	s_setprio 1
	s_barrier
	v_mfma_f32_16x16x32_bf16 v[62:65], v[140:143], v[194:197], v[62:65]
	v_mfma_f32_16x16x32_bf16 v[62:65], v[148:151], v[198:201], v[62:65]
	v_mfma_f32_16x16x32_bf16 v[54:57], v[148:151], v[206:209], v[54:57]
	v_mfma_f32_16x16x32_bf16 v[54:57], v[140:143], v[202:205], v[54:57]
	v_mfma_f32_16x16x32_bf16 v[38:41], v[140:143], v[228:231], v[38:41]
	v_mfma_f32_16x16x32_bf16 v[38:41], v[148:151], v[232:235], v[38:41]
	v_mfma_f32_16x16x32_bf16 v[22:25], v[148:151], v[240:243], v[22:25]
	v_mfma_f32_16x16x32_bf16 v[22:25], v[140:143], v[236:239], v[22:25]
	v_mfma_f32_16x16x32_bf16 v[14:17], v[152:155], v[236:239], v[14:17]
	v_mfma_f32_16x16x32_bf16 v[14:17], v[156:159], v[240:243], v[14:17]
	v_mfma_f32_16x16x32_bf16 v[30:33], v[156:159], v[232:235], v[30:33]
	v_mfma_f32_16x16x32_bf16 v[30:33], v[152:155], v[228:231], v[30:33]
	v_mfma_f32_16x16x32_bf16 v[46:49], v[152:155], v[202:205], v[46:49]
	v_mfma_f32_16x16x32_bf16 v[46:49], v[156:159], v[206:209], v[46:49]
	v_mfma_f32_16x16x32_bf16 v[58:61], v[156:159], v[198:201], v[58:61]
	v_mfma_f32_16x16x32_bf16 v[58:61], v[152:155], v[194:197], v[58:61]
	v_mfma_f32_16x16x32_bf16 v[50:53], v[160:163], v[194:197], v[50:53]
	v_mfma_f32_16x16x32_bf16 v[50:53], v[164:167], v[198:201], v[50:53]
	v_mfma_f32_16x16x32_bf16 v[34:37], v[164:167], v[206:209], v[34:37]
	v_mfma_f32_16x16x32_bf16 v[34:37], v[160:163], v[202:205], v[34:37]
	v_mfma_f32_16x16x32_bf16 v[18:21], v[160:163], v[228:231], v[18:21]
	v_mfma_f32_16x16x32_bf16 v[18:21], v[164:167], v[232:235], v[18:21]
	v_mfma_f32_16x16x32_bf16 v[6:9], v[164:167], v[240:243], v[6:9]
	v_mfma_f32_16x16x32_bf16 v[6:9], v[160:163], v[236:239], v[6:9]
	v_mfma_f32_16x16x32_bf16 v[2:5], v[168:171], v[236:239], v[2:5]
	v_mfma_f32_16x16x32_bf16 v[2:5], v[190:193], v[240:243], v[2:5]
	v_mfma_f32_16x16x32_bf16 v[10:13], v[190:193], v[232:235], v[10:13]
	v_mfma_f32_16x16x32_bf16 v[10:13], v[168:171], v[228:231], v[10:13]
	v_mfma_f32_16x16x32_bf16 v[26:29], v[168:171], v[202:205], v[26:29]
	v_mfma_f32_16x16x32_bf16 v[26:29], v[190:193], v[206:209], v[26:29]
	v_mfma_f32_16x16x32_bf16 v[42:45], v[190:193], v[198:201], v[42:45]
	v_mfma_f32_16x16x32_bf16 v[42:45], v[168:171], v[194:197], v[42:45]
	s_barrier
	s_setprio 0
	s_cmp_gt_u32 s48, 61
	s_cbranch_scc0 .LBB0_139
	s_and_b64 vcc, exec, s[4:5]
	s_cbranch_vccz .LBB0_142
	s_barrier

.LBB0_575:
	s_add_i32 s53, 0, 0x10000
	v_add_u32_e32 v140, s53, v143
	s_add_i32 s56, 0, 0x14000
	ds_read_b128 v[146:149], v140
	ds_read_b128 v[150:153], v140 offset:1024
	ds_read_b128 v[154:157], v140 offset:2048
	ds_read_b128 v[158:161], v140 offset:3072
	v_add_u32_e32 v140, s56, v143
	ds_read_b128 v[162:165], v140
	ds_read_b128 v[166:169], v140 offset:1024
	ds_read_b128 v[170:173], v140 offset:2048
	ds_read_b128 v[178:181], v140 offset:3072
	v_lshl_add_u64 v[140:141], s[18:19], 0, v[136:137]
	s_add_i32 m0, s39, 0xc000
	ds_read_b128 v[190:193], v145
	ds_read_b128 v[194:197], v145 offset:1024
	ds_read_b128 v[198:201], v145 offset:2048
	ds_read_b128 v[202:205], v145 offset:3072
	ds_read_b128 v[206:209], v145 offset:4096
	ds_read_b128 v[228:231], v145 offset:5120
	ds_read_b128 v[232:235], v145 offset:6144
	ds_read_b128 v[236:239], v145 offset:7168
	global_load_lds_dwordx4 v[140:141], off
	v_lshl_add_u64 v[140:141], s[18:19], 0, v[138:139]
	s_add_i32 m0, s39, 0xe000
	s_nop 0
	global_load_lds_dwordx4 v[140:141], off
	s_waitcnt vmcnt(8)
	s_waitcnt lgkmcnt(0)
	s_setprio 1
	s_barrier
	v_mfma_f32_16x16x32_bf16 v[126:129], v[146:149], v[190:193], v[126:129]
	v_mfma_f32_16x16x32_bf16 v[126:129], v[150:153], v[194:197], v[126:129]
	v_mfma_f32_16x16x32_bf16 v[118:121], v[150:153], v[202:205], v[118:121]
	v_mfma_f32_16x16x32_bf16 v[118:121], v[146:149], v[198:201], v[118:121]
	v_mfma_f32_16x16x32_bf16 v[102:105], v[146:149], v[206:209], v[102:105]
	v_mfma_f32_16x16x32_bf16 v[102:105], v[150:153], v[228:231], v[102:105]
	v_mfma_f32_16x16x32_bf16 v[86:89], v[150:153], v[236:239], v[86:89]
	v_mfma_f32_16x16x32_bf16 v[86:89], v[146:149], v[232:235], v[86:89]
	v_mfma_f32_16x16x32_bf16 v[78:81], v[154:157], v[232:235], v[78:81]
	v_mfma_f32_16x16x32_bf16 v[78:81], v[158:161], v[236:239], v[78:81]
	v_mfma_f32_16x16x32_bf16 v[94:97], v[158:161], v[228:231], v[94:97]
	v_mfma_f32_16x16x32_bf16 v[94:97], v[154:157], v[206:209], v[94:97]
	v_mfma_f32_16x16x32_bf16 v[110:113], v[154:157], v[198:201], v[110:113]
	v_mfma_f32_16x16x32_bf16 v[110:113], v[158:161], v[202:205], v[110:113]
	v_mfma_f32_16x16x32_bf16 v[122:125], v[158:161], v[194:197], v[122:125]
	v_mfma_f32_16x16x32_bf16 v[122:125], v[154:157], v[190:193], v[122:125]
	v_mfma_f32_16x16x32_bf16 v[114:117], v[162:165], v[190:193], v[114:117]
	v_mfma_f32_16x16x32_bf16 v[114:117], v[166:169], v[194:197], v[114:117]
	v_mfma_f32_16x16x32_bf16 v[98:101], v[166:169], v[202:205], v[98:101]
	v_mfma_f32_16x16x32_bf16 v[98:101], v[162:165], v[198:201], v[98:101]
	v_mfma_f32_16x16x32_bf16 v[82:85], v[162:165], v[206:209], v[82:85]
	v_mfma_f32_16x16x32_bf16 v[82:85], v[166:169], v[228:231], v[82:85]
	v_mfma_f32_16x16x32_bf16 v[70:73], v[166:169], v[236:239], v[70:73]
	v_mfma_f32_16x16x32_bf16 v[70:73], v[162:165], v[232:235], v[70:73]
	v_mfma_f32_16x16x32_bf16 v[66:69], v[170:173], v[232:235], v[66:69]
	v_mfma_f32_16x16x32_bf16 v[66:69], v[178:181], v[236:239], v[66:69]
	v_mfma_f32_16x16x32_bf16 v[74:77], v[178:181], v[228:231], v[74:77]
	v_mfma_f32_16x16x32_bf16 v[74:77], v[170:173], v[206:209], v[74:77]
	v_mfma_f32_16x16x32_bf16 v[90:93], v[170:173], v[198:201], v[90:93]
	v_mfma_f32_16x16x32_bf16 v[90:93], v[178:181], v[202:205], v[90:93]
	v_mfma_f32_16x16x32_bf16 v[106:109], v[178:181], v[194:197], v[106:109]
	v_mfma_f32_16x16x32_bf16 v[106:109], v[170:173], v[190:193], v[106:109]
	s_barrier
	s_setprio 0
	s_add_i32 s53, s53, s38
	v_lshl_add_u64 v[140:141], s[22:23], 0, v[0:1]
	s_mov_b32 m0, s53
	s_nop 0
	global_load_lds_dwordx4 v[140:141], off
	ds_read_b128 v[190:193], v145 offset:16384
	ds_read_b128 v[194:197], v145 offset:17408
	s_add_i32 m0, s53, 0x2000
	s_add_u32 s54, s22, 0x100000
	v_lshl_add_u64 v[186:187], s[22:23], 0, v[130:131]
	s_addc_u32 s55, s23, 0
	s_add_i32 s53, s56, s38
	global_load_lds_dwordx4 v[186:187], off
	ds_read_b128 v[198:201], v145 offset:18432
	ds_read_b128 v[202:205], v145 offset:19456
	v_lshl_add_u64 v[188:189], s[54:55], 0, v[0:1]
	s_mov_b32 m0, s53
	v_lshl_add_u64 v[210:211], s[24:25], 0, v[132:133]
	global_load_lds_dwordx4 v[188:189], off
	ds_read_b128 v[206:209], v145 offset:20480
	ds_read_b128 v[228:231], v145 offset:21504
	v_lshl_add_u64 v[188:189], s[54:55], 0, v[130:131]
	s_add_i32 m0, s53, 0x2000
	s_nop 0
	global_load_lds_dwordx4 v[188:189], off
	ds_read_b128 v[232:235], v145 offset:22528
	ds_read_b128 v[236:239], v145 offset:23552
	v_lshl_add_u64 v[188:189], s[24:25], 0, v[134:135]
	s_mov_b32 m0, s39
	s_nop 0
	global_load_lds_dwordx4 v[188:189], off
	s_mov_b32 m0, s40
	s_nop 0
	global_load_lds_dwordx4 v[210:211], off
	s_waitcnt vmcnt(8)
	s_waitcnt lgkmcnt(0)
	s_setprio 1
	s_barrier
	v_mfma_f32_16x16x32_bf16 v[62:65], v[146:149], v[190:193], v[62:65]
	v_mfma_f32_16x16x32_bf16 v[62:65], v[150:153], v[194:197], v[62:65]
	v_mfma_f32_16x16x32_bf16 v[54:57], v[150:153], v[202:205], v[54:57]
	v_mfma_f32_16x16x32_bf16 v[54:57], v[146:149], v[198:201], v[54:57]
	v_mfma_f32_16x16x32_bf16 v[38:41], v[146:149], v[206:209], v[38:41]
	v_mfma_f32_16x16x32_bf16 v[38:41], v[150:153], v[228:231], v[38:41]
	v_mfma_f32_16x16x32_bf16 v[22:25], v[150:153], v[236:239], v[22:25]
	v_mfma_f32_16x16x32_bf16 v[22:25], v[146:149], v[232:235], v[22:25]
	v_mfma_f32_16x16x32_bf16 v[14:17], v[154:157], v[232:235], v[14:17]
	v_mfma_f32_16x16x32_bf16 v[14:17], v[158:161], v[236:239], v[14:17]
	v_mfma_f32_16x16x32_bf16 v[30:33], v[158:161], v[228:231], v[30:33]
	v_mfma_f32_16x16x32_bf16 v[30:33], v[154:157], v[206:209], v[30:33]
	v_mfma_f32_16x16x32_bf16 v[46:49], v[154:157], v[198:201], v[46:49]
	v_mfma_f32_16x16x32_bf16 v[46:49], v[158:161], v[202:205], v[46:49]
	v_mfma_f32_16x16x32_bf16 v[58:61], v[158:161], v[194:197], v[58:61]
	v_mfma_f32_16x16x32_bf16 v[58:61], v[154:157], v[190:193], v[58:61]
	v_mfma_f32_16x16x32_bf16 v[50:53], v[162:165], v[190:193], v[50:53]
	v_mfma_f32_16x16x32_bf16 v[50:53], v[166:169], v[194:197], v[50:53]
	v_mfma_f32_16x16x32_bf16 v[34:37], v[166:169], v[202:205], v[34:37]
	v_mfma_f32_16x16x32_bf16 v[34:37], v[162:165], v[198:201], v[34:37]
	v_mfma_f32_16x16x32_bf16 v[18:21], v[162:165], v[206:209], v[18:21]
	v_mfma_f32_16x16x32_bf16 v[18:21], v[166:169], v[228:231], v[18:21]
	v_mfma_f32_16x16x32_bf16 v[6:9], v[166:169], v[236:239], v[6:9]
	v_mfma_f32_16x16x32_bf16 v[6:9], v[162:165], v[232:235], v[6:9]
	v_mfma_f32_16x16x32_bf16 v[2:5], v[170:173], v[232:235], v[2:5]
	v_mfma_f32_16x16x32_bf16 v[2:5], v[178:181], v[236:239], v[2:5]
	v_mfma_f32_16x16x32_bf16 v[10:13], v[178:181], v[228:231], v[10:13]
	v_mfma_f32_16x16x32_bf16 v[10:13], v[170:173], v[206:209], v[10:13]
	v_mfma_f32_16x16x32_bf16 v[26:29], v[170:173], v[198:201], v[26:29]
	v_mfma_f32_16x16x32_bf16 v[26:29], v[178:181], v[202:205], v[26:29]
	v_mfma_f32_16x16x32_bf16 v[42:45], v[178:181], v[194:197], v[42:45]
	v_mfma_f32_16x16x32_bf16 v[42:45], v[170:173], v[190:193], v[42:45]
	s_barrier
	s_setprio 0
	s_add_i32 s53, 0, 0x18000
	s_add_i32 s54, 0, 0x1c000
	v_add_u32_e32 v158, s53, v143
	v_add_u32_e32 v175, s54, v143
	ds_read_b128 v[146:149], v158
	ds_read_b128 v[150:153], v158 offset:1024
	ds_read_b128 v[154:157], v158 offset:2048
	ds_read_b128 v[158:161], v158 offset:3072
	ds_read_b128 v[162:165], v175
	ds_read_b128 v[166:169], v175 offset:1024
	ds_read_b128 v[170:173], v175 offset:2048
	ds_read_b128 v[178:181], v175 offset:3072
	s_add_u32 s24, s24, 0x100000
	s_addc_u32 s25, s25, 0
	s_mov_b32 m0, s41
	v_lshl_add_u64 v[226:227], s[24:25], 0, v[134:135]
	ds_read_b128 v[190:193], v145 offset:32768
	ds_read_b128 v[194:197], v145 offset:33792
	ds_read_b128 v[198:201], v145 offset:34816
	ds_read_b128 v[202:205], v145 offset:35840
	ds_read_b128 v[206:209], v145 offset:36864
	ds_read_b128 v[228:231], v145 offset:37888
	ds_read_b128 v[232:235], v145 offset:38912
	ds_read_b128 v[236:239], v145 offset:39936
	global_load_lds_dwordx4 v[226:227], off
	v_lshl_add_u64 v[226:227], s[24:25], 0, v[132:133]
	s_mov_b32 m0, s42
	s_nop 0
	global_load_lds_dwordx4 v[226:227], off
	s_waitcnt vmcnt(8)
	s_waitcnt lgkmcnt(0)
	s_setprio 1
	s_barrier
	v_mfma_f32_16x16x32_bf16 v[126:129], v[146:149], v[190:193], v[126:129]
	v_mfma_f32_16x16x32_bf16 v[126:129], v[150:153], v[194:197], v[126:129]
	v_mfma_f32_16x16x32_bf16 v[118:121], v[150:153], v[202:205], v[118:121]
	v_mfma_f32_16x16x32_bf16 v[118:121], v[146:149], v[198:201], v[118:121]
	v_mfma_f32_16x16x32_bf16 v[102:105], v[146:149], v[206:209], v[102:105]
	v_mfma_f32_16x16x32_bf16 v[102:105], v[150:153], v[228:231], v[102:105]
	v_mfma_f32_16x16x32_bf16 v[86:89], v[150:153], v[236:239], v[86:89]
	v_mfma_f32_16x16x32_bf16 v[86:89], v[146:149], v[232:235], v[86:89]
	v_mfma_f32_16x16x32_bf16 v[78:81], v[154:157], v[232:235], v[78:81]
	v_mfma_f32_16x16x32_bf16 v[78:81], v[158:161], v[236:239], v[78:81]
	v_mfma_f32_16x16x32_bf16 v[94:97], v[158:161], v[228:231], v[94:97]
	v_mfma_f32_16x16x32_bf16 v[94:97], v[154:157], v[206:209], v[94:97]
	v_mfma_f32_16x16x32_bf16 v[110:113], v[154:157], v[198:201], v[110:113]
	v_mfma_f32_16x16x32_bf16 v[110:113], v[158:161], v[202:205], v[110:113]
	v_mfma_f32_16x16x32_bf16 v[122:125], v[158:161], v[194:197], v[122:125]
	v_mfma_f32_16x16x32_bf16 v[122:125], v[154:157], v[190:193], v[122:125]
	v_mfma_f32_16x16x32_bf16 v[114:117], v[162:165], v[190:193], v[114:117]
	v_mfma_f32_16x16x32_bf16 v[114:117], v[166:169], v[194:197], v[114:117]
	v_mfma_f32_16x16x32_bf16 v[98:101], v[166:169], v[202:205], v[98:101]
	v_mfma_f32_16x16x32_bf16 v[98:101], v[162:165], v[198:201], v[98:101]
	v_mfma_f32_16x16x32_bf16 v[82:85], v[162:165], v[206:209], v[82:85]
	v_mfma_f32_16x16x32_bf16 v[82:85], v[166:169], v[228:231], v[82:85]
	v_mfma_f32_16x16x32_bf16 v[70:73], v[166:169], v[236:239], v[70:73]
	v_mfma_f32_16x16x32_bf16 v[70:73], v[162:165], v[232:235], v[70:73]
	v_mfma_f32_16x16x32_bf16 v[66:69], v[170:173], v[232:235], v[66:69]
	v_mfma_f32_16x16x32_bf16 v[66:69], v[178:181], v[236:239], v[66:69]
	v_mfma_f32_16x16x32_bf16 v[74:77], v[178:181], v[228:231], v[74:77]
	v_mfma_f32_16x16x32_bf16 v[74:77], v[170:173], v[206:209], v[74:77]
	v_mfma_f32_16x16x32_bf16 v[90:93], v[170:173], v[198:201], v[90:93]
	v_mfma_f32_16x16x32_bf16 v[90:93], v[178:181], v[202:205], v[90:93]
	v_mfma_f32_16x16x32_bf16 v[106:109], v[178:181], v[194:197], v[106:109]
	v_mfma_f32_16x16x32_bf16 v[106:109], v[170:173], v[190:193], v[106:109]
	s_barrier
	s_setprio 0
	s_add_i32 s24, s53, s38
	v_lshl_add_u64 v[140:141], v[140:141], 0, s[34:35]
	s_mov_b32 m0, s24
	s_nop 0
	global_load_lds_dwordx4 v[140:141], off
	ds_read_b128 v[190:193], v145 offset:49152
	ds_read_b128 v[194:197], v145 offset:50176
	s_add_i32 m0, s24, 0x2000
	s_add_u32 s22, s22, 0x100080
	v_lshl_add_u64 v[140:141], v[186:187], 0, s[34:35]
	s_addc_u32 s23, s23, 0
	s_add_i32 s24, s54, s38
	global_load_lds_dwordx4 v[140:141], off
	ds_read_b128 v[198:201], v145 offset:51200
	ds_read_b128 v[202:205], v145 offset:52224
	v_lshl_add_u64 v[140:141], s[22:23], 0, v[0:1]
	s_mov_b32 m0, s24
	s_nop 0
	global_load_lds_dwordx4 v[140:141], off
	ds_read_b128 v[206:209], v145 offset:53248
	ds_read_b128 v[228:231], v145 offset:54272
	v_lshl_add_u64 v[140:141], s[22:23], 0, v[130:131]
	s_add_i32 m0, s24, 0x2000
	s_nop 0
	global_load_lds_dwordx4 v[140:141], off
	ds_read_b128 v[232:235], v145 offset:55296
	ds_read_b128 v[236:239], v145 offset:56320
	v_lshl_add_u64 v[140:141], v[188:189], 0, s[34:35]
	s_mov_b32 m0, s43
	s_nop 0
	global_load_lds_dwordx4 v[140:141], off
	s_add_i32 s52, s52, 2
	s_add_u32 s18, s18, 0x100
	s_addc_u32 s19, s19, 0
	s_add_u32 s50, s50, 0x100
	s_addc_u32 s51, s51, 0
	s_add_u32 s22, s18, 0xfff00080
	s_addc_u32 s23, s19, -1
	s_cmp_eq_u32 s52, 60
	s_cselect_b32 s25, s9, s23
	s_cselect_b32 s24, s48, s22
	s_cselect_b32 s23, s7, s51
	s_cselect_b32 s22, s49, s50
	v_lshl_add_u64 v[140:141], v[210:211], 0, s[34:35]
	s_mov_b32 m0, s44
	s_nop 0
	global_load_lds_dwordx4 v[140:141], off
	s_waitcnt vmcnt(8)
	s_waitcnt lgkmcnt(0)
	s_setprio 1
	s_barrier
	v_mfma_f32_16x16x32_bf16 v[62:65], v[146:149], v[190:193], v[62:65]
	v_mfma_f32_16x16x32_bf16 v[62:65], v[150:153], v[194:197], v[62:65]
	v_mfma_f32_16x16x32_bf16 v[54:57], v[150:153], v[202:205], v[54:57]
	v_mfma_f32_16x16x32_bf16 v[54:57], v[146:149], v[198:201], v[54:57]
	v_mfma_f32_16x16x32_bf16 v[38:41], v[146:149], v[206:209], v[38:41]
	v_mfma_f32_16x16x32_bf16 v[38:41], v[150:153], v[228:231], v[38:41]
	v_mfma_f32_16x16x32_bf16 v[22:25], v[150:153], v[236:239], v[22:25]
	v_mfma_f32_16x16x32_bf16 v[22:25], v[146:149], v[232:235], v[22:25]
	v_mfma_f32_16x16x32_bf16 v[14:17], v[154:157], v[232:235], v[14:17]
	v_mfma_f32_16x16x32_bf16 v[14:17], v[158:161], v[236:239], v[14:17]
	v_mfma_f32_16x16x32_bf16 v[30:33], v[158:161], v[228:231], v[30:33]
	v_mfma_f32_16x16x32_bf16 v[30:33], v[154:157], v[206:209], v[30:33]
	v_mfma_f32_16x16x32_bf16 v[46:49], v[154:157], v[198:201], v[46:49]
	v_mfma_f32_16x16x32_bf16 v[46:49], v[158:161], v[202:205], v[46:49]
	v_mfma_f32_16x16x32_bf16 v[58:61], v[158:161], v[194:197], v[58:61]
	v_mfma_f32_16x16x32_bf16 v[58:61], v[154:157], v[190:193], v[58:61]
	v_mfma_f32_16x16x32_bf16 v[50:53], v[162:165], v[190:193], v[50:53]
	v_mfma_f32_16x16x32_bf16 v[50:53], v[166:169], v[194:197], v[50:53]
	v_mfma_f32_16x16x32_bf16 v[34:37], v[166:169], v[202:205], v[34:37]
	v_mfma_f32_16x16x32_bf16 v[34:37], v[162:165], v[198:201], v[34:37]
	v_mfma_f32_16x16x32_bf16 v[18:21], v[162:165], v[206:209], v[18:21]
	v_mfma_f32_16x16x32_bf16 v[18:21], v[166:169], v[228:231], v[18:21]
	v_mfma_f32_16x16x32_bf16 v[6:9], v[166:169], v[236:239], v[6:9]
	v_mfma_f32_16x16x32_bf16 v[6:9], v[162:165], v[232:235], v[6:9]
	v_mfma_f32_16x16x32_bf16 v[2:5], v[170:173], v[232:235], v[2:5]
	v_mfma_f32_16x16x32_bf16 v[2:5], v[178:181], v[236:239], v[2:5]
	v_mfma_f32_16x16x32_bf16 v[10:13], v[178:181], v[228:231], v[10:13]
	v_mfma_f32_16x16x32_bf16 v[10:13], v[170:173], v[206:209], v[10:13]
	v_mfma_f32_16x16x32_bf16 v[26:29], v[170:173], v[198:201], v[26:29]
	v_mfma_f32_16x16x32_bf16 v[26:29], v[178:181], v[202:205], v[26:29]
	v_mfma_f32_16x16x32_bf16 v[42:45], v[178:181], v[194:197], v[42:45]
	v_mfma_f32_16x16x32_bf16 v[42:45], v[170:173], v[190:193], v[42:45]
	s_barrier
	s_setprio 0
	s_cmp_gt_u32 s52, 61
	s_cbranch_scc0 .LBB0_575
	s_and_b64 vcc, exec, s[4:5]
	s_cbranch_vccz .LBB0_578
	s_barrier

.LBB0_721:
	s_add_i32 s53, 0, 0x10000
	v_add_u32_e32 v140, s53, v143
	s_add_i32 s56, 0, 0x14000
	ds_read_b128 v[146:149], v140
	ds_read_b128 v[150:153], v140 offset:1024
	ds_read_b128 v[154:157], v140 offset:2048
	ds_read_b128 v[158:161], v140 offset:3072
	v_add_u32_e32 v140, s56, v143
	ds_read_b128 v[162:165], v140
	ds_read_b128 v[166:169], v140 offset:1024
	ds_read_b128 v[170:173], v140 offset:2048
	ds_read_b128 v[178:181], v140 offset:3072
	v_lshl_add_u64 v[140:141], s[16:17], 0, v[136:137]
	s_add_i32 m0, s31, 0xc000
	ds_read_b128 v[190:193], v145
	ds_read_b128 v[194:197], v145 offset:1024
	ds_read_b128 v[198:201], v145 offset:2048
	ds_read_b128 v[202:205], v145 offset:3072
	ds_read_b128 v[206:209], v145 offset:4096
	ds_read_b128 v[228:231], v145 offset:5120
	ds_read_b128 v[232:235], v145 offset:6144
	ds_read_b128 v[236:239], v145 offset:7168
	global_load_lds_dwordx4 v[140:141], off
	v_lshl_add_u64 v[140:141], s[16:17], 0, v[138:139]
	s_add_i32 m0, s31, 0xe000
	s_nop 0
	global_load_lds_dwordx4 v[140:141], off
	s_waitcnt vmcnt(8)
	s_waitcnt lgkmcnt(0)
	s_setprio 1
	s_barrier
	v_mfma_f32_16x16x32_bf16 v[126:129], v[146:149], v[190:193], v[126:129]
	v_mfma_f32_16x16x32_bf16 v[126:129], v[150:153], v[194:197], v[126:129]
	v_mfma_f32_16x16x32_bf16 v[110:113], v[150:153], v[202:205], v[110:113]
	v_mfma_f32_16x16x32_bf16 v[110:113], v[146:149], v[198:201], v[110:113]
	v_mfma_f32_16x16x32_bf16 v[94:97], v[146:149], v[206:209], v[94:97]
	v_mfma_f32_16x16x32_bf16 v[94:97], v[150:153], v[228:231], v[94:97]
	v_mfma_f32_16x16x32_bf16 v[78:81], v[150:153], v[236:239], v[78:81]
	v_mfma_f32_16x16x32_bf16 v[78:81], v[146:149], v[232:235], v[78:81]
	v_mfma_f32_16x16x32_bf16 v[70:73], v[154:157], v[232:235], v[70:73]
	v_mfma_f32_16x16x32_bf16 v[70:73], v[158:161], v[236:239], v[70:73]
	v_mfma_f32_16x16x32_bf16 v[86:89], v[158:161], v[228:231], v[86:89]
	v_mfma_f32_16x16x32_bf16 v[86:89], v[154:157], v[206:209], v[86:89]
	v_mfma_f32_16x16x32_bf16 v[102:105], v[154:157], v[198:201], v[102:105]
	v_mfma_f32_16x16x32_bf16 v[102:105], v[158:161], v[202:205], v[102:105]
	v_mfma_f32_16x16x32_bf16 v[118:121], v[158:161], v[194:197], v[118:121]
	v_mfma_f32_16x16x32_bf16 v[118:121], v[154:157], v[190:193], v[118:121]
	v_mfma_f32_16x16x32_bf16 v[122:125], v[162:165], v[190:193], v[122:125]
	v_mfma_f32_16x16x32_bf16 v[122:125], v[166:169], v[194:197], v[122:125]
	v_mfma_f32_16x16x32_bf16 v[106:109], v[166:169], v[202:205], v[106:109]
	v_mfma_f32_16x16x32_bf16 v[106:109], v[162:165], v[198:201], v[106:109]
	v_mfma_f32_16x16x32_bf16 v[90:93], v[162:165], v[206:209], v[90:93]
	v_mfma_f32_16x16x32_bf16 v[90:93], v[166:169], v[228:231], v[90:93]
	v_mfma_f32_16x16x32_bf16 v[74:77], v[166:169], v[236:239], v[74:77]
	v_mfma_f32_16x16x32_bf16 v[74:77], v[162:165], v[232:235], v[74:77]
	v_mfma_f32_16x16x32_bf16 v[66:69], v[170:173], v[232:235], v[66:69]
	v_mfma_f32_16x16x32_bf16 v[66:69], v[178:181], v[236:239], v[66:69]
	v_mfma_f32_16x16x32_bf16 v[82:85], v[178:181], v[228:231], v[82:85]
	v_mfma_f32_16x16x32_bf16 v[82:85], v[170:173], v[206:209], v[82:85]
	v_mfma_f32_16x16x32_bf16 v[98:101], v[170:173], v[198:201], v[98:101]
	v_mfma_f32_16x16x32_bf16 v[98:101], v[178:181], v[202:205], v[98:101]
	v_mfma_f32_16x16x32_bf16 v[114:117], v[178:181], v[194:197], v[114:117]
	v_mfma_f32_16x16x32_bf16 v[114:117], v[170:173], v[190:193], v[114:117]
	s_barrier
	s_setprio 0
	s_add_i32 s53, s53, s26
	v_lshl_add_u64 v[140:141], s[18:19], 0, v[0:1]
	s_mov_b32 m0, s53
	s_nop 0
	global_load_lds_dwordx4 v[140:141], off
	ds_read_b128 v[190:193], v145 offset:16384
	ds_read_b128 v[194:197], v145 offset:17408
	s_add_i32 m0, s53, 0x2000
	s_add_u32 s54, s18, 0x100000
	v_lshl_add_u64 v[186:187], s[18:19], 0, v[130:131]
	s_addc_u32 s55, s19, 0
	s_add_i32 s53, s56, s26
	global_load_lds_dwordx4 v[186:187], off
	ds_read_b128 v[198:201], v145 offset:18432
	ds_read_b128 v[202:205], v145 offset:19456
	v_lshl_add_u64 v[188:189], s[54:55], 0, v[0:1]
	s_mov_b32 m0, s53
	v_lshl_add_u64 v[210:211], s[22:23], 0, v[132:133]
	global_load_lds_dwordx4 v[188:189], off
	ds_read_b128 v[206:209], v145 offset:20480
	ds_read_b128 v[228:231], v145 offset:21504
	v_lshl_add_u64 v[188:189], s[54:55], 0, v[130:131]
	s_add_i32 m0, s53, 0x2000
	s_nop 0
	global_load_lds_dwordx4 v[188:189], off
	ds_read_b128 v[232:235], v145 offset:22528
	ds_read_b128 v[236:239], v145 offset:23552
	v_lshl_add_u64 v[188:189], s[22:23], 0, v[134:135]
	s_mov_b32 m0, s31
	s_nop 0
	global_load_lds_dwordx4 v[188:189], off
	s_mov_b32 m0, s40
	s_nop 0
	global_load_lds_dwordx4 v[210:211], off
	s_waitcnt vmcnt(8)
	s_waitcnt lgkmcnt(0)
	s_setprio 1
	s_barrier
	v_mfma_f32_16x16x32_bf16 v[62:65], v[146:149], v[190:193], v[62:65]
	v_mfma_f32_16x16x32_bf16 v[62:65], v[150:153], v[194:197], v[62:65]
	v_mfma_f32_16x16x32_bf16 v[46:49], v[150:153], v[202:205], v[46:49]
	v_mfma_f32_16x16x32_bf16 v[46:49], v[146:149], v[198:201], v[46:49]
	v_mfma_f32_16x16x32_bf16 v[30:33], v[146:149], v[206:209], v[30:33]
	v_mfma_f32_16x16x32_bf16 v[30:33], v[150:153], v[228:231], v[30:33]
	v_mfma_f32_16x16x32_bf16 v[14:17], v[150:153], v[236:239], v[14:17]
	v_mfma_f32_16x16x32_bf16 v[14:17], v[146:149], v[232:235], v[14:17]
	v_mfma_f32_16x16x32_bf16 v[6:9], v[154:157], v[232:235], v[6:9]
	v_mfma_f32_16x16x32_bf16 v[6:9], v[158:161], v[236:239], v[6:9]
	v_mfma_f32_16x16x32_bf16 v[22:25], v[158:161], v[228:231], v[22:25]
	v_mfma_f32_16x16x32_bf16 v[22:25], v[154:157], v[206:209], v[22:25]
	v_mfma_f32_16x16x32_bf16 v[38:41], v[154:157], v[198:201], v[38:41]
	v_mfma_f32_16x16x32_bf16 v[38:41], v[158:161], v[202:205], v[38:41]
	v_mfma_f32_16x16x32_bf16 v[54:57], v[158:161], v[194:197], v[54:57]
	v_mfma_f32_16x16x32_bf16 v[54:57], v[154:157], v[190:193], v[54:57]
	v_mfma_f32_16x16x32_bf16 v[58:61], v[162:165], v[190:193], v[58:61]
	v_mfma_f32_16x16x32_bf16 v[58:61], v[166:169], v[194:197], v[58:61]
	v_mfma_f32_16x16x32_bf16 v[42:45], v[166:169], v[202:205], v[42:45]
	v_mfma_f32_16x16x32_bf16 v[42:45], v[162:165], v[198:201], v[42:45]
	v_mfma_f32_16x16x32_bf16 v[26:29], v[162:165], v[206:209], v[26:29]
	v_mfma_f32_16x16x32_bf16 v[26:29], v[166:169], v[228:231], v[26:29]
	v_mfma_f32_16x16x32_bf16 v[10:13], v[166:169], v[236:239], v[10:13]
	v_mfma_f32_16x16x32_bf16 v[10:13], v[162:165], v[232:235], v[10:13]
	v_mfma_f32_16x16x32_bf16 v[2:5], v[170:173], v[232:235], v[2:5]
	v_mfma_f32_16x16x32_bf16 v[2:5], v[178:181], v[236:239], v[2:5]
	v_mfma_f32_16x16x32_bf16 v[18:21], v[178:181], v[228:231], v[18:21]
	v_mfma_f32_16x16x32_bf16 v[18:21], v[170:173], v[206:209], v[18:21]
	v_mfma_f32_16x16x32_bf16 v[34:37], v[170:173], v[198:201], v[34:37]
	v_mfma_f32_16x16x32_bf16 v[34:37], v[178:181], v[202:205], v[34:37]
	v_mfma_f32_16x16x32_bf16 v[50:53], v[178:181], v[194:197], v[50:53]
	v_mfma_f32_16x16x32_bf16 v[50:53], v[170:173], v[190:193], v[50:53]
	s_barrier
	s_setprio 0
	s_add_i32 s53, 0, 0x18000
	s_add_i32 s54, 0, 0x1c000
	v_add_u32_e32 v158, s53, v143
	v_add_u32_e32 v175, s54, v143
	ds_read_b128 v[146:149], v158
	ds_read_b128 v[150:153], v158 offset:1024
	ds_read_b128 v[154:157], v158 offset:2048
	ds_read_b128 v[158:161], v158 offset:3072
	ds_read_b128 v[162:165], v175
	ds_read_b128 v[166:169], v175 offset:1024
	ds_read_b128 v[170:173], v175 offset:2048
	ds_read_b128 v[178:181], v175 offset:3072
	s_add_u32 s22, s22, 0x100000
	s_addc_u32 s23, s23, 0
	s_mov_b32 m0, s41
	v_lshl_add_u64 v[226:227], s[22:23], 0, v[134:135]
	ds_read_b128 v[190:193], v145 offset:32768
	ds_read_b128 v[194:197], v145 offset:33792
	ds_read_b128 v[198:201], v145 offset:34816
	ds_read_b128 v[202:205], v145 offset:35840
	ds_read_b128 v[206:209], v145 offset:36864
	ds_read_b128 v[228:231], v145 offset:37888
	ds_read_b128 v[232:235], v145 offset:38912
	ds_read_b128 v[236:239], v145 offset:39936
	global_load_lds_dwordx4 v[226:227], off
	v_lshl_add_u64 v[226:227], s[22:23], 0, v[132:133]
	s_mov_b32 m0, s42
	s_nop 0
	global_load_lds_dwordx4 v[226:227], off
	s_waitcnt vmcnt(8)
	s_waitcnt lgkmcnt(0)
	s_setprio 1
	s_barrier
	v_mfma_f32_16x16x32_bf16 v[126:129], v[146:149], v[190:193], v[126:129]
	v_mfma_f32_16x16x32_bf16 v[126:129], v[150:153], v[194:197], v[126:129]
	v_mfma_f32_16x16x32_bf16 v[110:113], v[150:153], v[202:205], v[110:113]
	v_mfma_f32_16x16x32_bf16 v[110:113], v[146:149], v[198:201], v[110:113]
	v_mfma_f32_16x16x32_bf16 v[94:97], v[146:149], v[206:209], v[94:97]
	v_mfma_f32_16x16x32_bf16 v[94:97], v[150:153], v[228:231], v[94:97]
	v_mfma_f32_16x16x32_bf16 v[78:81], v[150:153], v[236:239], v[78:81]
	v_mfma_f32_16x16x32_bf16 v[78:81], v[146:149], v[232:235], v[78:81]
	v_mfma_f32_16x16x32_bf16 v[70:73], v[154:157], v[232:235], v[70:73]
	v_mfma_f32_16x16x32_bf16 v[70:73], v[158:161], v[236:239], v[70:73]
	v_mfma_f32_16x16x32_bf16 v[86:89], v[158:161], v[228:231], v[86:89]
	v_mfma_f32_16x16x32_bf16 v[86:89], v[154:157], v[206:209], v[86:89]
	v_mfma_f32_16x16x32_bf16 v[102:105], v[154:157], v[198:201], v[102:105]
	v_mfma_f32_16x16x32_bf16 v[102:105], v[158:161], v[202:205], v[102:105]
	v_mfma_f32_16x16x32_bf16 v[118:121], v[158:161], v[194:197], v[118:121]
	v_mfma_f32_16x16x32_bf16 v[118:121], v[154:157], v[190:193], v[118:121]
	v_mfma_f32_16x16x32_bf16 v[122:125], v[162:165], v[190:193], v[122:125]
	v_mfma_f32_16x16x32_bf16 v[122:125], v[166:169], v[194:197], v[122:125]
	v_mfma_f32_16x16x32_bf16 v[106:109], v[166:169], v[202:205], v[106:109]
	v_mfma_f32_16x16x32_bf16 v[106:109], v[162:165], v[198:201], v[106:109]
	v_mfma_f32_16x16x32_bf16 v[90:93], v[162:165], v[206:209], v[90:93]
	v_mfma_f32_16x16x32_bf16 v[90:93], v[166:169], v[228:231], v[90:93]
	v_mfma_f32_16x16x32_bf16 v[74:77], v[166:169], v[236:239], v[74:77]
	v_mfma_f32_16x16x32_bf16 v[74:77], v[162:165], v[232:235], v[74:77]
	v_mfma_f32_16x16x32_bf16 v[66:69], v[170:173], v[232:235], v[66:69]
	v_mfma_f32_16x16x32_bf16 v[66:69], v[178:181], v[236:239], v[66:69]
	v_mfma_f32_16x16x32_bf16 v[82:85], v[178:181], v[228:231], v[82:85]
	v_mfma_f32_16x16x32_bf16 v[82:85], v[170:173], v[206:209], v[82:85]
	v_mfma_f32_16x16x32_bf16 v[98:101], v[170:173], v[198:201], v[98:101]
	v_mfma_f32_16x16x32_bf16 v[98:101], v[178:181], v[202:205], v[98:101]
	v_mfma_f32_16x16x32_bf16 v[114:117], v[178:181], v[194:197], v[114:117]
	v_mfma_f32_16x16x32_bf16 v[114:117], v[170:173], v[190:193], v[114:117]
	s_barrier
	s_setprio 0
	s_add_i32 s22, s53, s26
	v_lshl_add_u64 v[140:141], v[140:141], 0, s[34:35]
	s_mov_b32 m0, s22
	s_nop 0
	global_load_lds_dwordx4 v[140:141], off
	ds_read_b128 v[190:193], v145 offset:49152
	ds_read_b128 v[194:197], v145 offset:50176
	s_add_i32 m0, s22, 0x2000
	s_add_u32 s18, s18, 0x100080
	v_lshl_add_u64 v[140:141], v[186:187], 0, s[34:35]
	s_addc_u32 s19, s19, 0
	s_add_i32 s22, s54, s26
	global_load_lds_dwordx4 v[140:141], off
	ds_read_b128 v[198:201], v145 offset:51200
	ds_read_b128 v[202:205], v145 offset:52224
	v_lshl_add_u64 v[140:141], s[18:19], 0, v[0:1]
	s_mov_b32 m0, s22
	s_nop 0
	global_load_lds_dwordx4 v[140:141], off
	ds_read_b128 v[206:209], v145 offset:53248
	ds_read_b128 v[228:231], v145 offset:54272
	v_lshl_add_u64 v[140:141], s[18:19], 0, v[130:131]
	s_add_i32 m0, s22, 0x2000
	s_nop 0
	global_load_lds_dwordx4 v[140:141], off
	ds_read_b128 v[232:235], v145 offset:55296
	ds_read_b128 v[236:239], v145 offset:56320
	v_lshl_add_u64 v[140:141], v[188:189], 0, s[34:35]
	s_mov_b32 m0, s43
	s_nop 0
	global_load_lds_dwordx4 v[140:141], off
	s_add_i32 s52, s52, 2
	s_add_u32 s16, s16, 0x100
	s_addc_u32 s17, s17, 0
	s_add_u32 s50, s50, 0x100
	s_addc_u32 s51, s51, 0
	s_add_u32 s18, s16, 0xfff00080
	s_addc_u32 s19, s17, -1
	s_cmp_eq_u32 s52, 60
	s_cselect_b32 s23, s7, s19
	s_cselect_b32 s22, s48, s18
	s_cselect_b32 s19, s5, s51
	s_cselect_b32 s18, s49, s50
	v_lshl_add_u64 v[140:141], v[210:211], 0, s[34:35]
	s_mov_b32 m0, s44
	s_nop 0
	global_load_lds_dwordx4 v[140:141], off
	s_waitcnt vmcnt(8)
	s_waitcnt lgkmcnt(0)
	s_setprio 1
	s_barrier
	v_mfma_f32_16x16x32_bf16 v[62:65], v[146:149], v[190:193], v[62:65]
	v_mfma_f32_16x16x32_bf16 v[62:65], v[150:153], v[194:197], v[62:65]
	v_mfma_f32_16x16x32_bf16 v[46:49], v[150:153], v[202:205], v[46:49]
	v_mfma_f32_16x16x32_bf16 v[46:49], v[146:149], v[198:201], v[46:49]
	v_mfma_f32_16x16x32_bf16 v[30:33], v[146:149], v[206:209], v[30:33]
	v_mfma_f32_16x16x32_bf16 v[30:33], v[150:153], v[228:231], v[30:33]
	v_mfma_f32_16x16x32_bf16 v[14:17], v[150:153], v[236:239], v[14:17]
	v_mfma_f32_16x16x32_bf16 v[14:17], v[146:149], v[232:235], v[14:17]
	v_mfma_f32_16x16x32_bf16 v[6:9], v[154:157], v[232:235], v[6:9]
	v_mfma_f32_16x16x32_bf16 v[6:9], v[158:161], v[236:239], v[6:9]
	v_mfma_f32_16x16x32_bf16 v[22:25], v[158:161], v[228:231], v[22:25]
	v_mfma_f32_16x16x32_bf16 v[22:25], v[154:157], v[206:209], v[22:25]
	v_mfma_f32_16x16x32_bf16 v[38:41], v[154:157], v[198:201], v[38:41]
	v_mfma_f32_16x16x32_bf16 v[38:41], v[158:161], v[202:205], v[38:41]
	v_mfma_f32_16x16x32_bf16 v[54:57], v[158:161], v[194:197], v[54:57]
	v_mfma_f32_16x16x32_bf16 v[54:57], v[154:157], v[190:193], v[54:57]
	v_mfma_f32_16x16x32_bf16 v[58:61], v[162:165], v[190:193], v[58:61]
	v_mfma_f32_16x16x32_bf16 v[58:61], v[166:169], v[194:197], v[58:61]
	v_mfma_f32_16x16x32_bf16 v[42:45], v[166:169], v[202:205], v[42:45]
	v_mfma_f32_16x16x32_bf16 v[42:45], v[162:165], v[198:201], v[42:45]
	v_mfma_f32_16x16x32_bf16 v[26:29], v[162:165], v[206:209], v[26:29]
	v_mfma_f32_16x16x32_bf16 v[26:29], v[166:169], v[228:231], v[26:29]
	v_mfma_f32_16x16x32_bf16 v[10:13], v[166:169], v[236:239], v[10:13]
	v_mfma_f32_16x16x32_bf16 v[10:13], v[162:165], v[232:235], v[10:13]
	v_mfma_f32_16x16x32_bf16 v[2:5], v[170:173], v[232:235], v[2:5]
	v_mfma_f32_16x16x32_bf16 v[2:5], v[178:181], v[236:239], v[2:5]
	v_mfma_f32_16x16x32_bf16 v[18:21], v[178:181], v[228:231], v[18:21]
	v_mfma_f32_16x16x32_bf16 v[18:21], v[170:173], v[206:209], v[18:21]
	v_mfma_f32_16x16x32_bf16 v[34:37], v[170:173], v[198:201], v[34:37]
	v_mfma_f32_16x16x32_bf16 v[34:37], v[178:181], v[202:205], v[34:37]
	v_mfma_f32_16x16x32_bf16 v[50:53], v[178:181], v[194:197], v[50:53]
	v_mfma_f32_16x16x32_bf16 v[50:53], v[170:173], v[190:193], v[50:53]
	s_barrier
	s_setprio 0
	s_cmp_gt_u32 s52, 61
	s_cbranch_scc0 .LBB0_721
	s_and_b64 vcc, exec, s[2:3]
	s_cbranch_vccz .LBB0_724
	s_barrier

.LBB0_805:
	s_add_i32 s49, 0, 0x10000
	v_add_u32_e32 v140, s49, v143
	s_add_i32 s50, 0, 0x14000
	ds_read_b128 v[146:149], v140
	ds_read_b128 v[150:153], v140 offset:1024
	ds_read_b128 v[154:157], v140 offset:2048
	ds_read_b128 v[158:161], v140 offset:3072
	v_add_u32_e32 v140, s50, v143
	ds_read_b128 v[162:165], v140
	ds_read_b128 v[166:169], v140 offset:1024
	ds_read_b128 v[170:173], v140 offset:2048
	ds_read_b128 v[178:181], v140 offset:3072
	v_lshl_add_u64 v[140:141], s[14:15], 0, v[136:137]
	s_add_i32 m0, s31, 0xc000
	ds_read_b128 v[190:193], v145
	ds_read_b128 v[194:197], v145 offset:1024
	ds_read_b128 v[198:201], v145 offset:2048
	ds_read_b128 v[202:205], v145 offset:3072
	ds_read_b128 v[206:209], v145 offset:4096
	ds_read_b128 v[228:231], v145 offset:5120
	ds_read_b128 v[232:235], v145 offset:6144
	ds_read_b128 v[236:239], v145 offset:7168
	global_load_lds_dwordx4 v[140:141], off
	v_lshl_add_u64 v[140:141], s[14:15], 0, v[138:139]
	s_add_i32 m0, s31, 0xe000
	s_nop 0
	global_load_lds_dwordx4 v[140:141], off
	s_waitcnt vmcnt(8)
	s_waitcnt lgkmcnt(0)
	s_setprio 1
	s_barrier
	v_mfma_f32_16x16x32_bf16 v[126:129], v[146:149], v[190:193], v[126:129]
	v_mfma_f32_16x16x32_bf16 v[126:129], v[150:153], v[194:197], v[126:129]
	v_mfma_f32_16x16x32_bf16 v[118:121], v[150:153], v[202:205], v[118:121]
	v_mfma_f32_16x16x32_bf16 v[118:121], v[146:149], v[198:201], v[118:121]
	v_mfma_f32_16x16x32_bf16 v[102:105], v[146:149], v[206:209], v[102:105]
	v_mfma_f32_16x16x32_bf16 v[102:105], v[150:153], v[228:231], v[102:105]
	v_mfma_f32_16x16x32_bf16 v[86:89], v[150:153], v[236:239], v[86:89]
	v_mfma_f32_16x16x32_bf16 v[86:89], v[146:149], v[232:235], v[86:89]
	v_mfma_f32_16x16x32_bf16 v[78:81], v[154:157], v[232:235], v[78:81]
	v_mfma_f32_16x16x32_bf16 v[78:81], v[158:161], v[236:239], v[78:81]
	v_mfma_f32_16x16x32_bf16 v[94:97], v[158:161], v[228:231], v[94:97]
	v_mfma_f32_16x16x32_bf16 v[94:97], v[154:157], v[206:209], v[94:97]
	v_mfma_f32_16x16x32_bf16 v[110:113], v[154:157], v[198:201], v[110:113]
	v_mfma_f32_16x16x32_bf16 v[110:113], v[158:161], v[202:205], v[110:113]
	v_mfma_f32_16x16x32_bf16 v[122:125], v[158:161], v[194:197], v[122:125]
	v_mfma_f32_16x16x32_bf16 v[122:125], v[154:157], v[190:193], v[122:125]
	v_mfma_f32_16x16x32_bf16 v[114:117], v[162:165], v[190:193], v[114:117]
	v_mfma_f32_16x16x32_bf16 v[114:117], v[166:169], v[194:197], v[114:117]
	v_mfma_f32_16x16x32_bf16 v[98:101], v[166:169], v[202:205], v[98:101]
	v_mfma_f32_16x16x32_bf16 v[98:101], v[162:165], v[198:201], v[98:101]
	v_mfma_f32_16x16x32_bf16 v[82:85], v[162:165], v[206:209], v[82:85]
	v_mfma_f32_16x16x32_bf16 v[82:85], v[166:169], v[228:231], v[82:85]
	v_mfma_f32_16x16x32_bf16 v[70:73], v[166:169], v[236:239], v[70:73]
	v_mfma_f32_16x16x32_bf16 v[70:73], v[162:165], v[232:235], v[70:73]
	v_mfma_f32_16x16x32_bf16 v[66:69], v[170:173], v[232:235], v[66:69]
	v_mfma_f32_16x16x32_bf16 v[66:69], v[178:181], v[236:239], v[66:69]
	v_mfma_f32_16x16x32_bf16 v[74:77], v[178:181], v[228:231], v[74:77]
	v_mfma_f32_16x16x32_bf16 v[74:77], v[170:173], v[206:209], v[74:77]
	v_mfma_f32_16x16x32_bf16 v[90:93], v[170:173], v[198:201], v[90:93]
	v_mfma_f32_16x16x32_bf16 v[90:93], v[178:181], v[202:205], v[90:93]
	v_mfma_f32_16x16x32_bf16 v[106:109], v[178:181], v[194:197], v[106:109]
	v_mfma_f32_16x16x32_bf16 v[106:109], v[170:173], v[190:193], v[106:109]
	s_barrier
	s_setprio 0
	s_add_i32 s14, s49, s26
	v_lshl_add_u64 v[140:141], s[18:19], 0, v[0:1]
	s_mov_b32 m0, s14
	s_nop 0
	global_load_lds_dwordx4 v[140:141], off
	ds_read_b128 v[190:193], v145 offset:16384
	ds_read_b128 v[194:197], v145 offset:17408
	s_add_i32 m0, s14, 0x2000
	s_add_u32 s14, s18, 0x2b0000
	v_lshl_add_u64 v[186:187], s[18:19], 0, v[130:131]
	s_addc_u32 s15, s19, 0
	s_add_i32 s49, s50, s26
	global_load_lds_dwordx4 v[186:187], off
	ds_read_b128 v[198:201], v145 offset:18432
	ds_read_b128 v[202:205], v145 offset:19456
	v_lshl_add_u64 v[188:189], s[14:15], 0, v[0:1]
	s_mov_b32 m0, s49
	v_lshl_add_u64 v[210:211], s[22:23], 0, v[132:133]
	global_load_lds_dwordx4 v[188:189], off
	ds_read_b128 v[206:209], v145 offset:20480
	ds_read_b128 v[228:231], v145 offset:21504
	v_lshl_add_u64 v[188:189], s[14:15], 0, v[130:131]
	s_add_i32 m0, s49, 0x2000
	s_nop 0
	global_load_lds_dwordx4 v[188:189], off
	ds_read_b128 v[232:235], v145 offset:22528
	ds_read_b128 v[236:239], v145 offset:23552
	v_lshl_add_u64 v[188:189], s[22:23], 0, v[134:135]
	s_mov_b32 m0, s31
	s_nop 0
	global_load_lds_dwordx4 v[188:189], off
	s_mov_b32 m0, s36
	s_nop 0
	global_load_lds_dwordx4 v[210:211], off
	s_waitcnt vmcnt(8)
	s_waitcnt lgkmcnt(0)
	s_setprio 1
	s_barrier
	v_mfma_f32_16x16x32_bf16 v[62:65], v[146:149], v[190:193], v[62:65]
	v_mfma_f32_16x16x32_bf16 v[62:65], v[150:153], v[194:197], v[62:65]
	v_mfma_f32_16x16x32_bf16 v[54:57], v[150:153], v[202:205], v[54:57]
	v_mfma_f32_16x16x32_bf16 v[54:57], v[146:149], v[198:201], v[54:57]
	v_mfma_f32_16x16x32_bf16 v[38:41], v[146:149], v[206:209], v[38:41]
	v_mfma_f32_16x16x32_bf16 v[38:41], v[150:153], v[228:231], v[38:41]
	v_mfma_f32_16x16x32_bf16 v[22:25], v[150:153], v[236:239], v[22:25]
	v_mfma_f32_16x16x32_bf16 v[22:25], v[146:149], v[232:235], v[22:25]
	v_mfma_f32_16x16x32_bf16 v[14:17], v[154:157], v[232:235], v[14:17]
	v_mfma_f32_16x16x32_bf16 v[14:17], v[158:161], v[236:239], v[14:17]
	v_mfma_f32_16x16x32_bf16 v[30:33], v[158:161], v[228:231], v[30:33]
	v_mfma_f32_16x16x32_bf16 v[30:33], v[154:157], v[206:209], v[30:33]
	v_mfma_f32_16x16x32_bf16 v[46:49], v[154:157], v[198:201], v[46:49]
	v_mfma_f32_16x16x32_bf16 v[46:49], v[158:161], v[202:205], v[46:49]
	v_mfma_f32_16x16x32_bf16 v[58:61], v[158:161], v[194:197], v[58:61]
	v_mfma_f32_16x16x32_bf16 v[58:61], v[154:157], v[190:193], v[58:61]
	v_mfma_f32_16x16x32_bf16 v[50:53], v[162:165], v[190:193], v[50:53]
	v_mfma_f32_16x16x32_bf16 v[50:53], v[166:169], v[194:197], v[50:53]
	v_mfma_f32_16x16x32_bf16 v[34:37], v[166:169], v[202:205], v[34:37]
	v_mfma_f32_16x16x32_bf16 v[34:37], v[162:165], v[198:201], v[34:37]
	v_mfma_f32_16x16x32_bf16 v[18:21], v[162:165], v[206:209], v[18:21]
	v_mfma_f32_16x16x32_bf16 v[18:21], v[166:169], v[228:231], v[18:21]
	v_mfma_f32_16x16x32_bf16 v[6:9], v[166:169], v[236:239], v[6:9]
	v_mfma_f32_16x16x32_bf16 v[6:9], v[162:165], v[232:235], v[6:9]
	v_mfma_f32_16x16x32_bf16 v[2:5], v[170:173], v[232:235], v[2:5]
	v_mfma_f32_16x16x32_bf16 v[2:5], v[178:181], v[236:239], v[2:5]
	v_mfma_f32_16x16x32_bf16 v[10:13], v[178:181], v[228:231], v[10:13]
	v_mfma_f32_16x16x32_bf16 v[10:13], v[170:173], v[206:209], v[10:13]
	v_mfma_f32_16x16x32_bf16 v[26:29], v[170:173], v[198:201], v[26:29]
	v_mfma_f32_16x16x32_bf16 v[26:29], v[178:181], v[202:205], v[26:29]
	v_mfma_f32_16x16x32_bf16 v[42:45], v[178:181], v[194:197], v[42:45]
	v_mfma_f32_16x16x32_bf16 v[42:45], v[170:173], v[190:193], v[42:45]
	s_barrier
	s_setprio 0
	s_add_i32 s49, 0, 0x18000
	s_add_i32 s50, 0, 0x1c000
	v_add_u32_e32 v158, s49, v143
	v_add_u32_e32 v175, s50, v143
	ds_read_b128 v[146:149], v158
	ds_read_b128 v[150:153], v158 offset:1024
	ds_read_b128 v[154:157], v158 offset:2048
	ds_read_b128 v[158:161], v158 offset:3072
	ds_read_b128 v[162:165], v175
	ds_read_b128 v[166:169], v175 offset:1024
	ds_read_b128 v[170:173], v175 offset:2048
	ds_read_b128 v[178:181], v175 offset:3072
	s_add_u32 s14, s22, 0x2b0000
	s_addc_u32 s15, s23, 0
	s_mov_b32 m0, s37
	v_lshl_add_u64 v[226:227], s[14:15], 0, v[134:135]
	ds_read_b128 v[190:193], v145 offset:32768
	ds_read_b128 v[194:197], v145 offset:33792
	ds_read_b128 v[198:201], v145 offset:34816
	ds_read_b128 v[202:205], v145 offset:35840
	ds_read_b128 v[206:209], v145 offset:36864
	ds_read_b128 v[228:231], v145 offset:37888
	ds_read_b128 v[232:235], v145 offset:38912
	ds_read_b128 v[236:239], v145 offset:39936
	global_load_lds_dwordx4 v[226:227], off
	v_lshl_add_u64 v[226:227], s[14:15], 0, v[132:133]
	s_mov_b32 m0, s38
	s_nop 0
	global_load_lds_dwordx4 v[226:227], off
	s_waitcnt vmcnt(8)
	s_waitcnt lgkmcnt(0)
	s_setprio 1
	s_barrier
	v_mfma_f32_16x16x32_bf16 v[126:129], v[146:149], v[190:193], v[126:129]
	v_mfma_f32_16x16x32_bf16 v[126:129], v[150:153], v[194:197], v[126:129]
	v_mfma_f32_16x16x32_bf16 v[118:121], v[150:153], v[202:205], v[118:121]
	v_mfma_f32_16x16x32_bf16 v[118:121], v[146:149], v[198:201], v[118:121]
	v_mfma_f32_16x16x32_bf16 v[102:105], v[146:149], v[206:209], v[102:105]
	v_mfma_f32_16x16x32_bf16 v[102:105], v[150:153], v[228:231], v[102:105]
	v_mfma_f32_16x16x32_bf16 v[86:89], v[150:153], v[236:239], v[86:89]
	v_mfma_f32_16x16x32_bf16 v[86:89], v[146:149], v[232:235], v[86:89]
	v_mfma_f32_16x16x32_bf16 v[78:81], v[154:157], v[232:235], v[78:81]
	v_mfma_f32_16x16x32_bf16 v[78:81], v[158:161], v[236:239], v[78:81]
	v_mfma_f32_16x16x32_bf16 v[94:97], v[158:161], v[228:231], v[94:97]
	v_mfma_f32_16x16x32_bf16 v[94:97], v[154:157], v[206:209], v[94:97]
	v_mfma_f32_16x16x32_bf16 v[110:113], v[154:157], v[198:201], v[110:113]
	v_mfma_f32_16x16x32_bf16 v[110:113], v[158:161], v[202:205], v[110:113]
	v_mfma_f32_16x16x32_bf16 v[122:125], v[158:161], v[194:197], v[122:125]
	v_mfma_f32_16x16x32_bf16 v[122:125], v[154:157], v[190:193], v[122:125]
	v_mfma_f32_16x16x32_bf16 v[114:117], v[162:165], v[190:193], v[114:117]
	v_mfma_f32_16x16x32_bf16 v[114:117], v[166:169], v[194:197], v[114:117]
	v_mfma_f32_16x16x32_bf16 v[98:101], v[166:169], v[202:205], v[98:101]
	v_mfma_f32_16x16x32_bf16 v[98:101], v[162:165], v[198:201], v[98:101]
	v_mfma_f32_16x16x32_bf16 v[82:85], v[162:165], v[206:209], v[82:85]
	v_mfma_f32_16x16x32_bf16 v[82:85], v[166:169], v[228:231], v[82:85]
	v_mfma_f32_16x16x32_bf16 v[70:73], v[166:169], v[236:239], v[70:73]
	v_mfma_f32_16x16x32_bf16 v[70:73], v[162:165], v[232:235], v[70:73]
	v_mfma_f32_16x16x32_bf16 v[66:69], v[170:173], v[232:235], v[66:69]
	v_mfma_f32_16x16x32_bf16 v[66:69], v[178:181], v[236:239], v[66:69]
	v_mfma_f32_16x16x32_bf16 v[74:77], v[178:181], v[228:231], v[74:77]
	v_mfma_f32_16x16x32_bf16 v[74:77], v[170:173], v[206:209], v[74:77]
	v_mfma_f32_16x16x32_bf16 v[90:93], v[170:173], v[198:201], v[90:93]
	v_mfma_f32_16x16x32_bf16 v[90:93], v[178:181], v[202:205], v[90:93]
	v_mfma_f32_16x16x32_bf16 v[106:109], v[178:181], v[194:197], v[106:109]
	v_mfma_f32_16x16x32_bf16 v[106:109], v[170:173], v[190:193], v[106:109]
	s_barrier
	s_setprio 0
	s_add_i32 s14, s49, s26
	v_lshl_add_u64 v[140:141], v[140:141], 0, s[34:35]
	s_mov_b32 m0, s14
	s_nop 0
	global_load_lds_dwordx4 v[140:141], off
	ds_read_b128 v[190:193], v145 offset:49152
	ds_read_b128 v[194:197], v145 offset:50176
	s_add_i32 m0, s14, 0x2000
	s_add_u32 s14, s18, 0x2b0080
	v_lshl_add_u64 v[140:141], v[186:187], 0, s[34:35]
	s_addc_u32 s15, s19, 0
	s_add_i32 s18, s50, s26
	global_load_lds_dwordx4 v[140:141], off
	ds_read_b128 v[198:201], v145 offset:51200
	ds_read_b128 v[202:205], v145 offset:52224
	v_lshl_add_u64 v[140:141], s[14:15], 0, v[0:1]
	s_mov_b32 m0, s18
	s_nop 0
	global_load_lds_dwordx4 v[140:141], off
	ds_read_b128 v[206:209], v145 offset:53248
	ds_read_b128 v[228:231], v145 offset:54272
	v_lshl_add_u64 v[140:141], s[14:15], 0, v[130:131]
	s_add_i32 m0, s18, 0x2000
	s_nop 0
	global_load_lds_dwordx4 v[140:141], off
	ds_read_b128 v[232:235], v145 offset:55296
	ds_read_b128 v[236:239], v145 offset:56320
	v_lshl_add_u64 v[140:141], v[188:189], 0, s[34:35]
	s_mov_b32 m0, s39
	s_nop 0
	global_load_lds_dwordx4 v[140:141], off
	s_add_i32 s48, s48, 2
	s_add_u32 s46, s46, 0x100
	s_addc_u32 s47, s47, 0
	s_mov_b64 s[14:15], s[16:17]
	s_add_u32 s16, s14, 0x100
	s_addc_u32 s17, s15, 0
	s_cmpk_eq_i32 s48, 0xa8
	s_cselect_b32 s23, s5, s17
	s_cselect_b32 s22, s4, s16
	s_cselect_b32 s19, s9, s47
	s_cselect_b32 s18, s8, s46
	v_lshl_add_u64 v[140:141], v[210:211], 0, s[34:35]
	s_mov_b32 m0, s40
	s_nop 0
	global_load_lds_dwordx4 v[140:141], off
	s_waitcnt vmcnt(8)
	s_waitcnt lgkmcnt(0)
	s_setprio 1
	s_barrier
	v_mfma_f32_16x16x32_bf16 v[62:65], v[146:149], v[190:193], v[62:65]
	v_mfma_f32_16x16x32_bf16 v[62:65], v[150:153], v[194:197], v[62:65]
	v_mfma_f32_16x16x32_bf16 v[54:57], v[150:153], v[202:205], v[54:57]
	v_mfma_f32_16x16x32_bf16 v[54:57], v[146:149], v[198:201], v[54:57]
	v_mfma_f32_16x16x32_bf16 v[38:41], v[146:149], v[206:209], v[38:41]
	v_mfma_f32_16x16x32_bf16 v[38:41], v[150:153], v[228:231], v[38:41]
	v_mfma_f32_16x16x32_bf16 v[22:25], v[150:153], v[236:239], v[22:25]
	v_mfma_f32_16x16x32_bf16 v[22:25], v[146:149], v[232:235], v[22:25]
	v_mfma_f32_16x16x32_bf16 v[14:17], v[154:157], v[232:235], v[14:17]
	v_mfma_f32_16x16x32_bf16 v[14:17], v[158:161], v[236:239], v[14:17]
	v_mfma_f32_16x16x32_bf16 v[30:33], v[158:161], v[228:231], v[30:33]
	v_mfma_f32_16x16x32_bf16 v[30:33], v[154:157], v[206:209], v[30:33]
	v_mfma_f32_16x16x32_bf16 v[46:49], v[154:157], v[198:201], v[46:49]
	v_mfma_f32_16x16x32_bf16 v[46:49], v[158:161], v[202:205], v[46:49]
	v_mfma_f32_16x16x32_bf16 v[58:61], v[158:161], v[194:197], v[58:61]
	v_mfma_f32_16x16x32_bf16 v[58:61], v[154:157], v[190:193], v[58:61]
	v_mfma_f32_16x16x32_bf16 v[50:53], v[162:165], v[190:193], v[50:53]
	v_mfma_f32_16x16x32_bf16 v[50:53], v[166:169], v[194:197], v[50:53]
	v_mfma_f32_16x16x32_bf16 v[34:37], v[166:169], v[202:205], v[34:37]
	v_mfma_f32_16x16x32_bf16 v[34:37], v[162:165], v[198:201], v[34:37]
	v_mfma_f32_16x16x32_bf16 v[18:21], v[162:165], v[206:209], v[18:21]
	v_mfma_f32_16x16x32_bf16 v[18:21], v[166:169], v[228:231], v[18:21]
	v_mfma_f32_16x16x32_bf16 v[6:9], v[166:169], v[236:239], v[6:9]
	v_mfma_f32_16x16x32_bf16 v[6:9], v[162:165], v[232:235], v[6:9]
	v_mfma_f32_16x16x32_bf16 v[2:5], v[170:173], v[232:235], v[2:5]
	v_mfma_f32_16x16x32_bf16 v[2:5], v[178:181], v[236:239], v[2:5]
	v_mfma_f32_16x16x32_bf16 v[10:13], v[178:181], v[228:231], v[10:13]
	v_mfma_f32_16x16x32_bf16 v[10:13], v[170:173], v[206:209], v[10:13]
	v_mfma_f32_16x16x32_bf16 v[26:29], v[170:173], v[198:201], v[26:29]
	v_mfma_f32_16x16x32_bf16 v[26:29], v[178:181], v[202:205], v[26:29]
	v_mfma_f32_16x16x32_bf16 v[42:45], v[178:181], v[194:197], v[42:45]
	v_mfma_f32_16x16x32_bf16 v[42:45], v[170:173], v[190:193], v[42:45]
	s_barrier
	s_setprio 0
	s_cmpk_gt_u32 s48, 0xa9
	s_cbranch_scc0 .LBB0_805
	s_and_b64 vcc, exec, s[6:7]
	s_cbranch_vccz .LBB0_808
	s_barrier
